# on-chip Z scan with 1040-byte LDS row stride (conflict-free accumulator writes), pre-scan L1 invalidate removed
# baseline (speedup 1.0000x reference)
; __device__ __forceinline__ unsigned cvt_pk_bf16(float lo, float hi) { unsigned r; asm volatile("v_cvt_pk_bf16_f32 %0, %1, %2" : "=v"(r) : "v"(lo), "v"(hi)); return r; }
; __device__ __forceinline__ void s5_carry2(const Params& P, int j, int g) {
;     int tid = threadIdx.x; asm volatile("" : "+v"(tid));
;     const int wid = __builtin_amdgcn_readfirstlane(tid >> 6), pp = tid & 63;
;     if (wid < 2) {
;         const int dir = wid; const int idx = ((j * 2 + dir) * 64 + g) * 64 + pp;
;         const f32x2 a32 = *(const f32x2*)(P.ws + WS_A32 + (size_t)idx * 8); const float ar = a32.x, ai = a32.y;
;         const float* zp = (const float*)(P.ws + WS_Z) + (size_t)(g * 256) * 256 + dir * 128 + pp;
;         bf16_t* up = (bf16_t*)(P.ws + WS_U2) + (size_t)g * 256 * 768 + 512 + dir * 128 + pp;
;         float cr = 0.f, cim = 0.f; float zr[8], zi[8], nzr[8], nzi[8];
; #pragma unroll
;         for (int u = 0; u < 8; ++u) { const int n = dir ? (255 - u) : u; zr[u] = zp[(size_t)n * 256]; zi[u] = zp[(size_t)n * 256 + 64]; }
;         for (int s0 = 0; s0 < 256; s0 += 8) {
;             if (s0 + 8 < 256) {
; #pragma unroll
;                 for (int u = 0; u < 8; ++u) { const int n = dir ? (255 - (s0 + 8 + u)) : (s0 + 8 + u); nzr[u] = zp[(size_t)n * 256]; nzi[u] = zp[(size_t)n * 256 + 64]; }
;             }
; #pragma unroll
;             for (int u = 0; u < 8; ++u) { const int n = dir ? (255 - (s0 + u)) : (s0 + u);
;                 up[(size_t)n * 768] = (bf16_t)(cvt_pk_bf16(cr, 0.f) & 0xffffu); up[(size_t)n * 768 + 64] = (bf16_t)(cvt_pk_bf16(cim, 0.f) & 0xffffu);
;                 const float nr = ar * cr - ai * cim + zr[u], ni = ar * cim + ai * cr + zi[u]; cr = nr; cim = ni; }
.LBB0_584:
	v_mov_b32_e32 v1, v200
	s_barrier
	s_waitcnt vmcnt(0)
	s_waitcnt vmcnt(0) lgkmcnt(0)
	s_barrier
	s_waitcnt vmcnt(0)
	s_nop 0
	v_readfirstlane_b32 s0, v1
	s_ashr_i32 s1, s0, 6
	v_and_b32_e32 v130, 63, v200
	v_and_b32_e32 v131, 15, v130
	v_lshrrev_b32_e32 v132, 4, v130
	s_lshr_b32 s12, s1, 2
	s_and_b32 s13, s1, 3
	s_mul_i32 s20, s12, 0x10400
	s_lshl_b32 s21, s13, 7
	s_add_i32 s20, s20, s21
	v_mul_u32_u24_e32 v133, 0x410, v131
	v_lshl_add_u32 v133, v132, 4, v133
	v_add_u32_e32 v133, s20, v133
	s_mul_i32 s20, s12, 0x10400
	s_sub_i32 s20, 0x142f0, s20
	s_add_i32 s20, s20, s21
	v_mul_u32_u24_e32 v134, 0x410, v131
	v_sub_u32_e32 v134, s20, v134
	v_lshl_add_u32 v134, v132, 4, v134
	s_cmp_gt_i32 s1, 1
	s_cbranch_scc1 .Lcarry_setup_done
	s_lshl_b32 s12, s70, 7
	s_lshl_b32 s23, s1, 6
	s_add_i32 s12, s12, s2
	s_add_i32 s12, s12, s23
	v_lshl_or_b32 v136, s12, 6, v130
	v_mov_b32_e32 v137, 0
	v_readlane_b32 s28, v254, 22
	v_readlane_b32 s29, v254, 23
	s_nop 1
	v_lshl_add_u64 v[136:137], v[136:137], 3, s[28:29]
	global_load_dwordx2 v[138:139], v[136:137], off
	s_lshl_b32 s23, s1, 9
	v_lshl_add_u32 v140, v130, 2, s23
	s_mul_i32 s26, s1, 0x5fb00
	v_lshl_add_u32 v141, v130, 1, s26
	s_mul_i32 s36, s1, 0xfffff400
	s_add_i32 s36, s36, 0x600
	v_readlane_b32 s34, v254, 28
	v_readlane_b32 s35, v254, 29
	v_mov_b32_e32 v142, 0
	v_mov_b32_e32 v143, 0
.Lcarry_setup_done:
	ds_write_b128 v133, v[126:129] offset:0
	ds_write_b128 v133, v[122:125] offset:64
	ds_write_b128 v133, v[118:121] offset:16640
	ds_write_b128 v133, v[114:117] offset:16704
	ds_write_b128 v133, v[106:109] offset:33280
	ds_write_b128 v133, v[98:101] offset:33344
	ds_write_b128 v133, v[90:93] offset:49920
	ds_write_b128 v133, v[82:85] offset:49984
	ds_write_b128 v134, v[46:49] offset:49920
	ds_write_b128 v134, v[42:45] offset:49984
	ds_write_b128 v134, v[30:33] offset:33280
	ds_write_b128 v134, v[26:29] offset:33344
	ds_write_b128 v134, v[14:17] offset:16640
	ds_write_b128 v134, v[10:13] offset:16704
	ds_write_b128 v134, v[6:9] offset:0
	ds_write_b128 v134, v[2:5] offset:64
	s_waitcnt vmcnt(0) lgkmcnt(0)
	s_barrier
	s_cmp_gt_i32 s1, 1
	s_cbranch_scc1 .Lcarry_skip0
	v_mov_b32_e32 v150, v140
	ds_read_b32 v170, v150 offset:0
	ds_read_b32 v171, v150 offset:256
	ds_read_b32 v172, v150 offset:1040
	ds_read_b32 v173, v150 offset:1296
	ds_read_b32 v174, v150 offset:2080
	ds_read_b32 v175, v150 offset:2336
	ds_read_b32 v176, v150 offset:3120
	ds_read_b32 v177, v150 offset:3376
	ds_read_b32 v178, v150 offset:4160
	ds_read_b32 v179, v150 offset:4416
	ds_read_b32 v180, v150 offset:5200
	ds_read_b32 v181, v150 offset:5456
	ds_read_b32 v182, v150 offset:6240
	ds_read_b32 v183, v150 offset:6496
	ds_read_b32 v184, v150 offset:7280
	ds_read_b32 v185, v150 offset:7536
	s_mov_b32 s12, 0
.Lcarry_loop0:
	s_waitcnt lgkmcnt(0)
	ds_read_b32 v186, v150 offset:8320
	ds_read_b32 v187, v150 offset:8576
	ds_read_b32 v188, v150 offset:9360
	ds_read_b32 v189, v150 offset:9616
	ds_read_b32 v190, v150 offset:10400
	ds_read_b32 v191, v150 offset:10656
	ds_read_b32 v192, v150 offset:11440
	ds_read_b32 v193, v150 offset:11696
	ds_read_b32 v194, v150 offset:12480
	ds_read_b32 v195, v150 offset:12736
	ds_read_b32 v196, v150 offset:13520
	ds_read_b32 v197, v150 offset:13776
	ds_read_b32 v198, v150 offset:14560
	ds_read_b32 v199, v150 offset:14816
	ds_read_b32 v210, v150 offset:15600
	ds_read_b32 v211, v150 offset:15856
	v_cvt_pk_bf16_f32 v144, v142, v143
	global_store_short v141, v144, s[34:35]
	global_store_short_d16_hi v141, v144, s[34:35] offset:128
	v_fma_f32 v146, v138, v142, v170
	v_fma_f32 v147, v138, v143, v171
	v_add_u32_e32 v141, s36, v141
	v_fma_f32 v148, -v139, v143, v146
	v_fma_f32 v149, v139, v142, v147
	v_cvt_pk_bf16_f32 v145, v148, v149
	global_store_short v141, v145, s[34:35]
	global_store_short_d16_hi v141, v145, s[34:35] offset:128
	v_fma_f32 v146, v138, v148, v172
	v_fma_f32 v147, v138, v149, v173
	v_add_u32_e32 v141, s36, v141
	v_fma_f32 v142, -v139, v149, v146
	v_fma_f32 v143, v139, v148, v147
	v_cvt_pk_bf16_f32 v144, v142, v143
	global_store_short v141, v144, s[34:35]
	global_store_short_d16_hi v141, v144, s[34:35] offset:128
	v_fma_f32 v146, v138, v142, v174
	v_fma_f32 v147, v138, v143, v175
	v_add_u32_e32 v141, s36, v141
	v_fma_f32 v148, -v139, v143, v146
	v_fma_f32 v149, v139, v142, v147
	v_cvt_pk_bf16_f32 v145, v148, v149
	global_store_short v141, v145, s[34:35]
	global_store_short_d16_hi v141, v145, s[34:35] offset:128
	v_fma_f32 v146, v138, v148, v176
	v_fma_f32 v147, v138, v149, v177
	v_add_u32_e32 v141, s36, v141
	v_fma_f32 v142, -v139, v149, v146
	v_fma_f32 v143, v139, v148, v147
	v_cvt_pk_bf16_f32 v144, v142, v143
	global_store_short v141, v144, s[34:35]
	global_store_short_d16_hi v141, v144, s[34:35] offset:128
	v_fma_f32 v146, v138, v142, v178
	v_fma_f32 v147, v138, v143, v179
	v_add_u32_e32 v141, s36, v141
	v_fma_f32 v148, -v139, v143, v146
	v_fma_f32 v149, v139, v142, v147
	v_cvt_pk_bf16_f32 v145, v148, v149
	global_store_short v141, v145, s[34:35]
	global_store_short_d16_hi v141, v145, s[34:35] offset:128
	v_fma_f32 v146, v138, v148, v180
	v_fma_f32 v147, v138, v149, v181
	v_add_u32_e32 v141, s36, v141
	v_fma_f32 v142, -v139, v149, v146
	v_fma_f32 v143, v139, v148, v147
	v_cvt_pk_bf16_f32 v144, v142, v143
	global_store_short v141, v144, s[34:35]
	global_store_short_d16_hi v141, v144, s[34:35] offset:128
	v_fma_f32 v146, v138, v142, v182
	v_fma_f32 v147, v138, v143, v183
	v_add_u32_e32 v141, s36, v141
	v_fma_f32 v148, -v139, v143, v146
	v_fma_f32 v149, v139, v142, v147
	v_cvt_pk_bf16_f32 v145, v148, v149
	global_store_short v141, v145, s[34:35]
	global_store_short_d16_hi v141, v145, s[34:35] offset:128
	v_fma_f32 v146, v138, v148, v184
	v_fma_f32 v147, v138, v149, v185
	v_add_u32_e32 v141, s36, v141
	v_fma_f32 v142, -v139, v149, v146
	v_fma_f32 v143, v139, v148, v147
	s_waitcnt lgkmcnt(0)
; __device__ __forceinline__ unsigned cvt_pk_bf16(float lo, float hi) { unsigned r; asm volatile("v_cvt_pk_bf16_f32 %0, %1, %2" : "=v"(r) : "v"(lo), "v"(hi)); return r; }
; __device__ __forceinline__ void s5_carry2(const Params& P, int j, int g) {
;     ...
;         for (int s0 = 0; s0 < 256; s0 += 8) {
;             if (s0 + 8 < 256) {
; #pragma unroll
;                 for (int u = 0; u < 8; ++u) { const int n = dir ? (255 - (s0 + 8 + u)) : (s0 + 8 + u); nzr[u] = zp[(size_t)n * 256]; nzi[u] = zp[(size_t)n * 256 + 64]; }
;             }
; #pragma unroll
;             for (int u = 0; u < 8; ++u) { const int n = dir ? (255 - (s0 + u)) : (s0 + u);
;                 up[(size_t)n * 768] = (bf16_t)(cvt_pk_bf16(cr, 0.f) & 0xffffu); up[(size_t)n * 768 + 64] = (bf16_t)(cvt_pk_bf16(cim, 0.f) & 0xffffu);
;                 const float nr = ar * cr - ai * cim + zr[u], ni = ar * cim + ai * cr + zi[u]; cr = nr; cim = ni; }
; #pragma unroll
;             for (int u = 0; u < 8; ++u) { zr[u] = nzr[u]; zi[u] = nzi[u]; }
;         }
	ds_read_b32 v170, v150 offset:16640
	ds_read_b32 v171, v150 offset:16896
	ds_read_b32 v172, v150 offset:17680
	ds_read_b32 v173, v150 offset:17936
	ds_read_b32 v174, v150 offset:18720
	ds_read_b32 v175, v150 offset:18976
	ds_read_b32 v176, v150 offset:19760
	ds_read_b32 v177, v150 offset:20016
	ds_read_b32 v178, v150 offset:20800
	ds_read_b32 v179, v150 offset:21056
	ds_read_b32 v180, v150 offset:21840
	ds_read_b32 v181, v150 offset:22096
	ds_read_b32 v182, v150 offset:22880
	ds_read_b32 v183, v150 offset:23136
	ds_read_b32 v184, v150 offset:23920
	ds_read_b32 v185, v150 offset:24176
	v_cvt_pk_bf16_f32 v144, v142, v143
	global_store_short v141, v144, s[34:35]
	global_store_short_d16_hi v141, v144, s[34:35] offset:128
	v_fma_f32 v146, v138, v142, v186
	v_fma_f32 v147, v138, v143, v187
	v_add_u32_e32 v141, s36, v141
	v_fma_f32 v148, -v139, v143, v146
	v_fma_f32 v149, v139, v142, v147
	v_cvt_pk_bf16_f32 v145, v148, v149
	global_store_short v141, v145, s[34:35]
	global_store_short_d16_hi v141, v145, s[34:35] offset:128
	v_fma_f32 v146, v138, v148, v188
	v_fma_f32 v147, v138, v149, v189
	v_add_u32_e32 v141, s36, v141
	v_fma_f32 v142, -v139, v149, v146
	v_fma_f32 v143, v139, v148, v147
	v_cvt_pk_bf16_f32 v144, v142, v143
	global_store_short v141, v144, s[34:35]
	global_store_short_d16_hi v141, v144, s[34:35] offset:128
	v_fma_f32 v146, v138, v142, v190
	v_fma_f32 v147, v138, v143, v191
	v_add_u32_e32 v141, s36, v141
	v_fma_f32 v148, -v139, v143, v146
	v_fma_f32 v149, v139, v142, v147
	v_cvt_pk_bf16_f32 v145, v148, v149
	global_store_short v141, v145, s[34:35]
	global_store_short_d16_hi v141, v145, s[34:35] offset:128
	v_fma_f32 v146, v138, v148, v192
	v_fma_f32 v147, v138, v149, v193
	v_add_u32_e32 v141, s36, v141
	v_fma_f32 v142, -v139, v149, v146
	v_fma_f32 v143, v139, v148, v147
	v_cvt_pk_bf16_f32 v144, v142, v143
	global_store_short v141, v144, s[34:35]
	global_store_short_d16_hi v141, v144, s[34:35] offset:128
	v_fma_f32 v146, v138, v142, v194
	v_fma_f32 v147, v138, v143, v195
	v_add_u32_e32 v141, s36, v141
	v_fma_f32 v148, -v139, v143, v146
	v_fma_f32 v149, v139, v142, v147
	v_cvt_pk_bf16_f32 v145, v148, v149
	global_store_short v141, v145, s[34:35]
	global_store_short_d16_hi v141, v145, s[34:35] offset:128
	v_fma_f32 v146, v138, v148, v196
	v_fma_f32 v147, v138, v149, v197
	v_add_u32_e32 v141, s36, v141
	v_fma_f32 v142, -v139, v149, v146
	v_fma_f32 v143, v139, v148, v147
	v_cvt_pk_bf16_f32 v144, v142, v143
	global_store_short v141, v144, s[34:35]
	global_store_short_d16_hi v141, v144, s[34:35] offset:128
	v_fma_f32 v146, v138, v142, v198
	v_fma_f32 v147, v138, v143, v199
	v_add_u32_e32 v141, s36, v141
	v_fma_f32 v148, -v139, v143, v146
	v_fma_f32 v149, v139, v142, v147
	v_cvt_pk_bf16_f32 v145, v148, v149
	global_store_short v141, v145, s[34:35]
	global_store_short_d16_hi v141, v145, s[34:35] offset:128
	v_fma_f32 v146, v138, v148, v210
	v_fma_f32 v147, v138, v149, v211
	v_add_u32_e32 v141, s36, v141
	v_fma_f32 v142, -v139, v149, v146
	v_fma_f32 v143, v139, v148, v147
	v_add_u32_e32 v150, 0x4100, v150
	s_add_i32 s12, s12, 1
	s_cmp_lt_u32 s12, 8
	s_cbranch_scc1 .Lcarry_loop0
	s_waitcnt lgkmcnt(0)
.Lcarry_skip0:
	s_barrier
	ds_write_b128 v133, v[62:65] offset:0
	ds_write_b128 v133, v[58:61] offset:64
	ds_write_b128 v133, v[54:57] offset:16640
	ds_write_b128 v133, v[50:53] offset:16704
	ds_write_b128 v133, v[38:41] offset:33280
	ds_write_b128 v133, v[34:37] offset:33344
	ds_write_b128 v133, v[22:25] offset:49920
	ds_write_b128 v133, v[18:21] offset:49984
	ds_write_b128 v134, v[110:113] offset:49920
	ds_write_b128 v134, v[102:105] offset:49984
	ds_write_b128 v134, v[94:97] offset:33280
	ds_write_b128 v134, v[86:89] offset:33344
	ds_write_b128 v134, v[78:81] offset:16640
	ds_write_b128 v134, v[74:77] offset:16704
	ds_write_b128 v134, v[70:73] offset:0
	ds_write_b128 v134, v[66:69] offset:64
	s_waitcnt lgkmcnt(0)
	s_barrier
	s_cmp_gt_i32 s1, 1
	s_cbranch_scc1 .Lcarry_skip1
	v_mov_b32_e32 v150, v140
	ds_read_b32 v170, v150 offset:0
	ds_read_b32 v171, v150 offset:256
	ds_read_b32 v172, v150 offset:1040
	ds_read_b32 v173, v150 offset:1296
	ds_read_b32 v174, v150 offset:2080
	ds_read_b32 v175, v150 offset:2336
	ds_read_b32 v176, v150 offset:3120
	ds_read_b32 v177, v150 offset:3376
	ds_read_b32 v178, v150 offset:4160
	ds_read_b32 v179, v150 offset:4416
	ds_read_b32 v180, v150 offset:5200
	ds_read_b32 v181, v150 offset:5456
	ds_read_b32 v182, v150 offset:6240
	ds_read_b32 v183, v150 offset:6496
	ds_read_b32 v184, v150 offset:7280
	ds_read_b32 v185, v150 offset:7536
	s_mov_b32 s12, 0
